# adds: attention softmax drops the redundant v_max x,x,x canonicalisations (72 VALU per key block)
# speedup vs baseline: 1.0226x; 1.0069x over previous
; __device__ __forceinline__ unsigned cvt_pk_bf16(float lo, float hi) { unsigned r; asm volatile("v_cvt_pk_bf16_f32 %0, %1, %2" : "=v"(r) : "v"(lo), "v"(hi)); return r; }
; #define LAS __attribute__((address_space(3)))
; __device__ __forceinline__ unsigned cvt_pk_bf16(float lo, float hi) { f32x2_t v = {lo, hi}; bf16x2_t b = __builtin_convertvector(v, bf16x2_t); return __builtin_bit_cast(unsigned, b); }
; __device__ __forceinline__ float fexp(float x) { return __builtin_amdgcn_exp2f(1.4426950408889634f * x); }
; #define MMA16(b, a, c) __builtin_amdgcn_mfma_f32_16x16x32_bf16((b), (a), (c), 0, 0, 0)
; __device__ __forceinline__ void attn_phase(const Params& p, LAS unsigned char* lds, int G) {
;     ...
;                 for (int n = 0; n < 4; ++n) { f32x4 a = (f32x4){0.f, 0.f, 0.f, 0.f}; a = MMA16(kf[n][0], qf[m][0], a); a = MMA16(kf[n][1], qf[m][1], a); s[n] = a; }
;                 const int i = row0 + 16 * m + fr; float mx = mrow[m];
;                 if (edge) {
; #pragma unroll
;                     for (int n = 0; n < 4; ++n)
; #pragma unroll
;                         for (int e = 0; e < 4; ++e) { const int j = kstart + 16 * n + 4 * fq + e, dlt = i - j; const bool valid = (dlt <= 128) && (dlt >= -128); s[n][e] = valid ? s[n][e] : -1e30f; }
;                 }
; #pragma unroll
;                 for (int n = 0; n < 4; ++n) mx = fmaxf(fmaxf(mx, fmaxf(s[n][0], s[n][1])), fmaxf(s[n][2], s[n][3]));
;                 mx = fmaxf(mx, __shfl_xor(mx, 16)); mx = fmaxf(mx, __shfl_xor(mx, 32));
;                 const float alpha = fexp(mrow[m] - mx); mrow[m] = mx; float ps = 0.f; const float mxl = mx * 1.4426950408889634f;
; #pragma unroll
;                 for (int n = 0; n < 4; ++n) {
;                     f32x4 pvv;
; #pragma unroll
;                     for (int e = 0; e < 4; ++e) { pvv[e] = __builtin_amdgcn_exp2f(s[n][e] * 1.4426950408889634f - mxl); ps += pvv[e]; }
;                     u32x2 w; w.x = cvt_pk_bf16(pvv[0], pvv[1]); w.y = cvt_pk_bf16(pvv[2], pvv[3]);
;                     *(LAS u32x2*)(Pl + (16 * m + fr) * 72 + 16 * n + 4 * fq) = w;
;                     o[m][n] = o[m][n] * alpha;
;                 }
;                 ps += __shfl_xor(ps, 16); ps += __shfl_xor(ps, 32);
;                 lrow[m] = lrow[m] * alpha + ps;
.LBB0_552:
	v_max_f32_e32 v175, v172, v173
	v_max_f32_e32 v193, v174, v192
	v_max3_f32 v175, v232, v175, v193
	v_max_f32_e32 v193, v168, v169
	v_max_f32_e32 v194, v170, v171
	v_max3_f32 v175, v175, v193, v194
	v_max_f32_e32 v193, v164, v165
	v_max_f32_e32 v194, v166, v167
	v_max3_f32 v175, v175, v193, v194
	v_max_f32_e32 v193, v160, v161
	v_max_f32_e32 v194, v162, v163
	v_max3_f32 v175, v175, v193, v194
	ds_bpermute_b32 v193, v222, v175
	v_add_u32_e32 v238, v205, v209
	s_andn2_b64 vcc, exec, s[12:13]
	s_waitcnt lgkmcnt(0)
	v_max_f32_e32 v175, v175, v193
	ds_bpermute_b32 v193, v223, v175
	s_waitcnt lgkmcnt(0)
	v_max_f32_e32 v193, v175, v193
	v_pk_mul_f32 v[194:195], v[192:193], s[6:7] op_sel_hi:[1,0]
	s_nop 0
	v_fma_f32 v172, v172, s6, -v195
	v_exp_f32_e32 v172, v172
	v_fma_f32 v173, v173, s6, -v195
	v_exp_f32_e32 v173, v173
	v_fma_f32 v174, v174, s6, -v195
	v_exp_f32_e32 v174, v174
	v_sub_f32_e32 v175, v194, v195
	v_exp_f32_e32 v175, v175
	v_fma_f32 v168, v168, s6, -v195
	v_add_f32_e32 v192, 0, v172
	v_exp_f32_e32 v168, v168
	v_fma_f32 v169, v169, s6, -v195
	v_fma_f32 v170, v170, s6, -v195
	v_fma_f32 v171, v171, s6, -v195
	v_add_f32_e32 v192, v173, v192
	v_exp_f32_e32 v169, v169
	v_exp_f32_e32 v170, v170
	v_exp_f32_e32 v171, v171
	v_add_f32_e32 v192, v174, v192
	v_add_f32_e32 v192, v175, v192
	v_cvt_pk_bf16_f32 v172, v172, v173
	v_cvt_pk_bf16_f32 v173, v174, v175
	v_add_f32_e32 v174, v168, v192
	v_add_f32_e32 v174, v169, v174
	v_cvt_pk_bf16_f32 v168, v168, v169
	v_cvt_pk_bf16_f32 v169, v170, v171
	v_add_u32_e32 v192, 0x9000, v238
	v_fma_f32 v164, v164, s6, -v195
	ds_write2_b64 v192, v[172:173], v[168:169] offset1:4
	v_exp_f32_e32 v168, v164
	v_fma_f32 v164, v165, s6, -v195
	v_exp_f32_e32 v169, v164
	v_fma_f32 v164, v166, s6, -v195
	v_add_f32_e32 v174, v170, v174
	v_exp_f32_e32 v170, v164
	v_fma_f32 v164, v167, s6, -v195
	v_add_f32_e32 v174, v171, v174
	v_exp_f32_e32 v171, v164
	v_fma_f32 v160, v160, s6, -v195
	v_add_f32_e32 v164, v168, v174
	v_exp_f32_e32 v194, v160
	v_fma_f32 v161, v161, s6, -v195
	v_add_f32_e32 v164, v169, v164
	v_exp_f32_e32 v234, v161
	v_fma_f32 v161, v162, s6, -v195
	v_add_f32_e32 v164, v170, v164
	v_exp_f32_e32 v237, v161
	v_fma_f32 v161, v163, s6, -v195
	v_add_f32_e32 v172, v171, v164
	v_mfma_f32_16x16x32_bf16 v[164:167], v[140:143], v[104:107], 0
	v_exp_f32_e32 v195, v161
	v_add_f32_e32 v160, v194, v172
	v_add_f32_e32 v160, v234, v160
	v_add_f32_e32 v160, v237, v160
	v_mfma_f32_16x16x32_bf16 v[172:175], v[132:135], v[108:111], v[164:167]
	v_add_f32_e32 v239, v195, v160
	ds_bpermute_b32 v240, v222, v239
	v_cvt_pk_bf16_f32 v196, v168, v169
	v_mfma_f32_16x16x32_bf16 v[164:167], v[156:159], v[104:107], 0
	v_cvt_pk_bf16_f32 v197, v170, v171
	v_cvt_pk_bf16_f32 v194, v194, v234
	v_cvt_pk_bf16_f32 v195, v237, v195
	v_mfma_f32_16x16x32_bf16 v[160:163], v[152:155], v[104:107], 0
	ds_write2_b64 v192, v[196:197], v[194:195] offset0:8 offset1:12
	s_waitcnt lgkmcnt(1)
	v_add_f32_e32 v192, v239, v240
	ds_bpermute_b32 v234, v223, v192
	v_mfma_f32_16x16x32_bf16 v[168:171], v[148:151], v[108:111], v[164:167]
	v_cndmask_b32_e64 v194, 0, 1, s[12:13]
	v_cmp_ne_u32_e64 s[2:3], 1, v194
	v_mfma_f32_16x16x32_bf16 v[164:167], v[144:147], v[108:111], v[160:163]
	v_mfma_f32_16x16x32_bf16 v[160:163], v[136:139], v[104:107], 0
	v_mfma_f32_16x16x32_bf16 v[160:163], v[128:131], v[108:111], v[160:163]
	s_cbranch_vccz .LBB0_554
	v_mov_b32_e32 v194, v175
	s_branch .LBB0_555

; __device__ __forceinline__ unsigned cvt_pk_bf16(float lo, float hi) { unsigned r; asm volatile("v_cvt_pk_bf16_f32 %0, %1, %2" : "=v"(r) : "v"(lo), "v"(hi)); return r; }
; #define LAS __attribute__((address_space(3)))
; __device__ __forceinline__ unsigned cvt_pk_bf16(float lo, float hi) { f32x2_t v = {lo, hi}; bf16x2_t b = __builtin_convertvector(v, bf16x2_t); return __builtin_bit_cast(unsigned, b); }
; __device__ __forceinline__ float fexp(float x) { return __builtin_amdgcn_exp2f(1.4426950408889634f * x); }
; #define MMA16(b, a, c) __builtin_amdgcn_mfma_f32_16x16x32_bf16((b), (a), (c), 0, 0, 0)
; __device__ __forceinline__ void attn_phase(const Params& p, LAS unsigned char* lds, int G) {
;     ...
;                 for (int n = 0; n < 4; ++n) { f32x4 a = (f32x4){0.f, 0.f, 0.f, 0.f}; a = MMA16(kf[n][0], qf[m][0], a); a = MMA16(kf[n][1], qf[m][1], a); s[n] = a; }
;                 const int i = row0 + 16 * m + fr; float mx = mrow[m];
;                 if (edge) {
; #pragma unroll
;                     for (int n = 0; n < 4; ++n)
; #pragma unroll
;                         for (int e = 0; e < 4; ++e) { const int j = kstart + 16 * n + 4 * fq + e, dlt = i - j; const bool valid = (dlt <= 128) && (dlt >= -128); s[n][e] = valid ? s[n][e] : -1e30f; }
;                 }
; #pragma unroll
;                 for (int n = 0; n < 4; ++n) mx = fmaxf(fmaxf(mx, fmaxf(s[n][0], s[n][1])), fmaxf(s[n][2], s[n][3]));
;                 mx = fmaxf(mx, __shfl_xor(mx, 16)); mx = fmaxf(mx, __shfl_xor(mx, 32));
;                 const float alpha = fexp(mrow[m] - mx); mrow[m] = mx; float ps = 0.f; const float mxl = mx * 1.4426950408889634f;
; #pragma unroll
;                 for (int n = 0; n < 4; ++n) {
;                     f32x4 pvv;
; #pragma unroll
;                     for (int e = 0; e < 4; ++e) { pvv[e] = __builtin_amdgcn_exp2f(s[n][e] * 1.4426950408889634f - mxl); ps += pvv[e]; }
;                     u32x2 w; w.x = cvt_pk_bf16(pvv[0], pvv[1]); w.y = cvt_pk_bf16(pvv[2], pvv[3]);
;                     *(LAS u32x2*)(Pl + (16 * m + fr) * 72 + 16 * n + 4 * fq) = w;
;                     o[m][n] = o[m][n] * alpha;
;                 }
;                 ps += __shfl_xor(ps, 16); ps += __shfl_xor(ps, 32);
;                 lrow[m] = lrow[m] * alpha + ps;
.LBB0_555:
	v_max_f32_e32 v175, v172, v173
	v_max_f32_e32 v195, v174, v194
	v_max3_f32 v175, v233, v175, v195
	v_max_f32_e32 v195, v168, v169
	v_max_f32_e32 v196, v170, v171
	v_max3_f32 v175, v175, v195, v196
	v_max_f32_e32 v195, v164, v165
	v_max_f32_e32 v196, v166, v167
	v_max3_f32 v175, v175, v195, v196
	v_max_f32_e32 v195, v160, v161
	v_max_f32_e32 v196, v162, v163
	v_max3_f32 v175, v175, v195, v196
	ds_bpermute_b32 v195, v222, v175
	s_and_b64 vcc, exec, s[2:3]
	s_waitcnt lgkmcnt(0)
	v_max_f32_e32 v175, v175, v195
	ds_bpermute_b32 v195, v223, v175
	s_waitcnt lgkmcnt(0)
	v_max_f32_e32 v195, v175, v195
	v_pk_mul_f32 v[196:197], v[194:195], s[6:7] op_sel_hi:[1,0]
	s_nop 0
	v_fma_f32 v172, v172, s6, -v197
	v_exp_f32_e32 v172, v172
	v_fma_f32 v173, v173, s6, -v197
	v_exp_f32_e32 v173, v173
	v_fma_f32 v174, v174, s6, -v197
	v_exp_f32_e32 v174, v174
	v_sub_f32_e32 v175, v196, v197
	v_exp_f32_e32 v175, v175
	v_fma_f32 v168, v168, s6, -v197
	v_add_f32_e32 v194, 0, v172
	v_exp_f32_e32 v168, v168
	v_fma_f32 v169, v169, s6, -v197
	v_fma_f32 v170, v170, s6, -v197
	v_fma_f32 v171, v171, s6, -v197
	v_add_f32_e32 v194, v173, v194
	v_exp_f32_e32 v169, v169
	v_exp_f32_e32 v170, v170
	v_exp_f32_e32 v171, v171
	v_add_f32_e32 v194, v174, v194
	v_add_f32_e32 v194, v175, v194
	v_cvt_pk_bf16_f32 v172, v172, v173
	v_cvt_pk_bf16_f32 v173, v174, v175
	v_add_f32_e32 v174, v168, v194
	v_add_f32_e32 v174, v169, v174
	v_cvt_pk_bf16_f32 v168, v168, v169
	v_cvt_pk_bf16_f32 v169, v170, v171
	v_add_u32_e32 v194, 0x9800, v238
	v_fma_f32 v164, v164, s6, -v197
	ds_write2_b64 v194, v[172:173], v[168:169] offset0:32 offset1:36
	v_exp_f32_e32 v168, v164
	v_fma_f32 v164, v165, s6, -v197
	v_exp_f32_e32 v169, v164
	v_fma_f32 v164, v166, s6, -v197
	v_add_f32_e32 v174, v170, v174
	v_exp_f32_e32 v170, v164
	v_fma_f32 v164, v167, s6, -v197
	v_add_f32_e32 v174, v171, v174
	v_exp_f32_e32 v171, v164
	v_add_f32_e32 v164, v168, v174
	v_add_f32_e32 v164, v169, v164
	v_add_f32_e32 v164, v170, v164
	v_add_f32_e32 v196, v171, v164
	v_mfma_f32_16x16x32_bf16 v[164:167], v[140:143], v[112:115], 0
	v_fma_f32 v160, v160, s6, -v197
	v_exp_f32_e32 v237, v160
	v_fma_f32 v161, v161, s6, -v197
	v_mfma_f32_16x16x32_bf16 v[172:175], v[132:135], v[116:119], v[164:167]
	v_cvt_pk_bf16_f32 v240, v168, v169
	v_add_f32_e32 v160, v237, v196
	v_exp_f32_e32 v196, v161
	v_mfma_f32_16x16x32_bf16 v[164:167], v[156:159], v[112:115], 0
	v_fma_f32 v161, v162, s6, -v197
	v_exp_f32_e32 v239, v161
	v_fma_f32 v161, v163, s6, -v197
	v_cvt_pk_bf16_f32 v241, v170, v171
	v_mfma_f32_16x16x32_bf16 v[168:171], v[148:151], v[116:119], v[164:167]
	s_nop 2
	v_exp_f32_e32 v165, v161
	v_add_f32_e32 v164, v196, v160
	v_add_f32_e32 v164, v239, v164
	v_mfma_f32_16x16x32_bf16 v[160:163], v[152:155], v[112:115], 0
	v_add_f32_e32 v197, v165, v164
	ds_bpermute_b32 v242, v222, v197
	v_cvt_pk_bf16_f32 v164, v237, v196
	v_cvt_pk_bf16_f32 v165, v239, v165
	ds_write2_b64 v194, v[240:241], v[164:165] offset0:40 offset1:44
	v_mfma_f32_16x16x32_bf16 v[164:167], v[136:139], v[112:115], 0
	s_waitcnt lgkmcnt(1)
	v_add_f32_e32 v194, v197, v242
	ds_bpermute_b32 v237, v223, v194
	v_mfma_f32_16x16x32_bf16 v[160:163], v[144:147], v[116:119], v[160:163]
	v_mfma_f32_16x16x32_bf16 v[164:167], v[128:131], v[116:119], v[164:167]
	s_cbranch_vccz .LBB0_557
	v_mov_b32_e32 v196, v175
	s_branch .LBB0_558

; __device__ __forceinline__ unsigned cvt_pk_bf16(float lo, float hi) { unsigned r; asm volatile("v_cvt_pk_bf16_f32 %0, %1, %2" : "=v"(r) : "v"(lo), "v"(hi)); return r; }
; #define LAS __attribute__((address_space(3)))
; __device__ __forceinline__ unsigned cvt_pk_bf16(float lo, float hi) { f32x2_t v = {lo, hi}; bf16x2_t b = __builtin_convertvector(v, bf16x2_t); return __builtin_bit_cast(unsigned, b); }
; __device__ __forceinline__ float fexp(float x) { return __builtin_amdgcn_exp2f(1.4426950408889634f * x); }
; #define MMA16(b, a, c) __builtin_amdgcn_mfma_f32_16x16x32_bf16((b), (a), (c), 0, 0, 0)
; __device__ __forceinline__ void attn_phase(const Params& p, LAS unsigned char* lds, int G) {
;     ...
;                 for (int n = 0; n < 4; ++n) { f32x4 a = (f32x4){0.f, 0.f, 0.f, 0.f}; a = MMA16(kf[n][0], qf[m][0], a); a = MMA16(kf[n][1], qf[m][1], a); s[n] = a; }
;                 const int i = row0 + 16 * m + fr; float mx = mrow[m];
;                 if (edge) {
; #pragma unroll
;                     for (int n = 0; n < 4; ++n)
; #pragma unroll
;                         for (int e = 0; e < 4; ++e) { const int j = kstart + 16 * n + 4 * fq + e, dlt = i - j; const bool valid = (dlt <= 128) && (dlt >= -128); s[n][e] = valid ? s[n][e] : -1e30f; }
;                 }
; #pragma unroll
;                 for (int n = 0; n < 4; ++n) mx = fmaxf(fmaxf(mx, fmaxf(s[n][0], s[n][1])), fmaxf(s[n][2], s[n][3]));
;                 mx = fmaxf(mx, __shfl_xor(mx, 16)); mx = fmaxf(mx, __shfl_xor(mx, 32));
;                 const float alpha = fexp(mrow[m] - mx); mrow[m] = mx; float ps = 0.f; const float mxl = mx * 1.4426950408889634f;
; #pragma unroll
;                 for (int n = 0; n < 4; ++n) {
;                     f32x4 pvv;
; #pragma unroll
;                     for (int e = 0; e < 4; ++e) { pvv[e] = __builtin_amdgcn_exp2f(s[n][e] * 1.4426950408889634f - mxl); ps += pvv[e]; }
;                     u32x2 w; w.x = cvt_pk_bf16(pvv[0], pvv[1]); w.y = cvt_pk_bf16(pvv[2], pvv[3]);
;                     *(LAS u32x2*)(Pl + (16 * m + fr) * 72 + 16 * n + 4 * fq) = w;
;                     o[m][n] = o[m][n] * alpha;
;                 }
;                 ps += __shfl_xor(ps, 16); ps += __shfl_xor(ps, 32);
;                 lrow[m] = lrow[m] * alpha + ps;
.LBB0_558:
	v_max_f32_e32 v175, v172, v173
	v_max_f32_e32 v197, v174, v196
	v_max3_f32 v175, v235, v175, v197
	v_max_f32_e32 v197, v168, v169
	v_max_f32_e32 v239, v170, v171
	v_max3_f32 v175, v175, v197, v239
	v_max_f32_e32 v197, v160, v161
	v_max_f32_e32 v239, v162, v163
	v_max3_f32 v175, v175, v197, v239
	v_max_f32_e32 v197, v164, v165
	v_max_f32_e32 v239, v166, v167
	v_max3_f32 v175, v175, v197, v239
	ds_bpermute_b32 v197, v222, v175
	v_mfma_f32_16x16x32_bf16 v[140:143], v[140:143], v[120:123], 0
	s_and_b64 vcc, exec, s[2:3]
	s_waitcnt lgkmcnt(0)
	v_max_f32_e32 v175, v175, v197
	ds_bpermute_b32 v197, v223, v175
	s_waitcnt lgkmcnt(0)
	v_max_f32_e32 v197, v175, v197
	v_pk_mul_f32 v[240:241], v[196:197], s[6:7] op_sel_hi:[1,0]
	s_nop 0
	v_fma_f32 v172, v172, s6, -v241
	v_exp_f32_e32 v172, v172
	v_fma_f32 v173, v173, s6, -v241
	v_exp_f32_e32 v173, v173
	v_fma_f32 v174, v174, s6, -v241
	v_exp_f32_e32 v174, v174
	v_sub_f32_e32 v175, v240, v241
	v_exp_f32_e32 v175, v175
	v_fma_f32 v168, v168, s6, -v241
	v_add_f32_e32 v196, 0, v172
	v_exp_f32_e32 v168, v168
	v_fma_f32 v169, v169, s6, -v241
	v_add_f32_e32 v196, v173, v196
	v_exp_f32_e32 v169, v169
	v_fma_f32 v170, v170, s6, -v241
	v_fma_f32 v171, v171, s6, -v241
	v_add_f32_e32 v196, v174, v196
	v_exp_f32_e32 v170, v170
	v_exp_f32_e32 v171, v171
	v_add_f32_e32 v196, v175, v196
	v_cvt_pk_bf16_f32 v172, v172, v173
	v_cvt_pk_bf16_f32 v173, v174, v175
	v_add_f32_e32 v174, v168, v196
	v_fma_f32 v160, v160, s6, -v241
	v_add_f32_e32 v174, v169, v174
	v_exp_f32_e32 v160, v160
	v_fma_f32 v161, v161, s6, -v241
	v_add_f32_e32 v174, v170, v174
	v_cvt_pk_bf16_f32 v168, v168, v169
	v_cvt_pk_bf16_f32 v169, v170, v171
	v_add_u32_e32 v170, 0xa000, v238
	v_exp_f32_e32 v161, v161
	v_fma_f32 v162, v162, s6, -v241
	ds_write2_b64 v170, v[172:173], v[168:169] offset0:64 offset1:68
	v_exp_f32_e32 v169, v162
	v_fma_f32 v162, v163, s6, -v241
	v_add_f32_e32 v174, v171, v174
	v_exp_f32_e32 v171, v162
	v_add_f32_e32 v162, v160, v174
	v_add_f32_e32 v162, v161, v162
	v_add_f32_e32 v162, v169, v162
	v_add_f32_e32 v172, v171, v162
	v_fma_f32 v162, v164, s6, -v241
	v_exp_f32_e32 v164, v162
	v_cvt_pk_bf16_f32 v168, v160, v161
	v_mfma_f32_16x16x32_bf16 v[160:163], v[132:135], v[124:127], v[140:143]
	v_cvt_pk_bf16_f32 v169, v169, v171
	v_add_f32_e32 v171, v164, v172
	v_mfma_f32_16x16x32_bf16 v[132:135], v[156:159], v[120:123], 0
	v_fma_f32 v140, v165, s6, -v241
	v_exp_f32_e32 v156, v140
	v_fma_f32 v140, v166, s6, -v241
	v_exp_f32_e32 v157, v140
	v_mfma_f32_16x16x32_bf16 v[140:143], v[148:151], v[124:127], v[132:135]
	v_add_f32_e32 v149, v156, v171
	v_add_f32_e32 v149, v157, v149
	s_nop 0
	v_fma_f32 v132, v167, s6, -v241
	v_exp_f32_e32 v148, v132
	v_mfma_f32_16x16x32_bf16 v[132:135], v[152:155], v[120:123], 0
	v_add_f32_e32 v150, v148, v149
	ds_bpermute_b32 v151, v222, v150
	v_mfma_f32_16x16x32_bf16 v[132:135], v[144:147], v[124:127], v[132:135]
	v_cvt_pk_bf16_f32 v145, v157, v148
	v_cvt_pk_bf16_f32 v144, v164, v156
	ds_write2_b64 v170, v[168:169], v[144:145] offset0:72 offset1:76
	v_mfma_f32_16x16x32_bf16 v[146:149], v[136:139], v[120:123], 0
	s_waitcnt lgkmcnt(1)
	v_add_f32_e32 v139, v150, v151
	ds_bpermute_b32 v145, v223, v139
	v_mfma_f32_16x16x32_bf16 v[128:131], v[128:131], v[124:127], v[146:149]
	s_cbranch_vccz .LBB0_560
	s_nop 6
	v_mov_b32_e32 v136, v131
	s_branch .LBB0_561

; __device__ __forceinline__ unsigned cvt_pk_bf16(float lo, float hi) { unsigned r; asm volatile("v_cvt_pk_bf16_f32 %0, %1, %2" : "=v"(r) : "v"(lo), "v"(hi)); return r; }
; #define LAS __attribute__((address_space(3)))
; __device__ __forceinline__ void attn_phase(const Params& p, LAS unsigned char* lds, int G) {
;     ...
;                 const int i = row0 + 16 * m + fr; float mx = mrow[m];
;                 if (edge) {
; #pragma unroll
;                     for (int n = 0; n < 4; ++n)
; #pragma unroll
;                         for (int e = 0; e < 4; ++e) { const int j = kstart + 16 * n + 4 * fq + e, dlt = i - j; const bool valid = (dlt <= 128) && (dlt >= -128); s[n][e] = valid ? s[n][e] : -1e30f; }
;                 }
; #pragma unroll
;                 for (int n = 0; n < 4; ++n) mx = fmaxf(fmaxf(mx, fmaxf(s[n][0], s[n][1])), fmaxf(s[n][2], s[n][3]));
;                 mx = fmaxf(mx, __shfl_xor(mx, 16)); mx = fmaxf(mx, __shfl_xor(mx, 32));
;                 const float alpha = fexp(mrow[m] - mx); mrow[m] = mx; float ps = 0.f; const float mxl = mx * 1.4426950408889634f;
; #pragma unroll
;                 for (int n = 0; n < 4; ++n) {
;                     f32x4 pvv;
; #pragma unroll
;                     for (int e = 0; e < 4; ++e) { pvv[e] = __builtin_amdgcn_exp2f(s[n][e] * 1.4426950408889634f - mxl); ps += pvv[e]; }
;                     u32x2 w; w.x = cvt_pk_bf16(pvv[0], pvv[1]); w.y = cvt_pk_bf16(pvv[2], pvv[3]);
;                     *(LAS u32x2*)(Pl + (16 * m + fr) * 72 + 16 * n + 4 * fq) = w;
;                     o[m][n] = o[m][n] * alpha;
;                 }
;                 ps += __shfl_xor(ps, 16); ps += __shfl_xor(ps, 32);
;                 lrow[m] = lrow[m] * alpha + ps;
;             }
;             asm volatile("s_waitcnt lgkmcnt(0)" ::: "memory");
;             {
; #pragma unroll
;                 for (int k = 0; k < 2; ++k) {
;                     bf16x8 pa[4], vb[4];
; #pragma unroll
;                     for (int m = 0; m < 4; ++m) pa[m] = LDS16(Pl + (16 * m + fr) * 72 + 32 * k + 8 * fq);
; #pragma unroll
;                     for (int n = 0; n < 4; ++n) vb[n] = tr_frag(Vl + (kvh * 64 + 32 * k) * 72 + trb + 16 * n, 72);
; #pragma unroll
;                     for (int n = 0; n < 4; ++n)
; #pragma unroll
;                         for (int m = 0; m < 4; ++m) o[m][n] = MMA16(vb[n], pa[m], o[m][n]);
.LBB0_561:
	v_sub_f32_e32 v131, v235, v197
	v_mul_f32_e32 v131, 0x3fb8aa3b, v131
	v_exp_f32_e32 v138, v131
	v_max_f32_e32 v131, v160, v161
	v_max_f32_e32 v137, v162, v163
	v_max3_f32 v131, v231, v131, v137
	v_max_f32_e32 v137, v140, v141
	v_max_f32_e32 v144, v142, v143
	v_max3_f32 v131, v131, v137, v144
	v_max_f32_e32 v137, v132, v133
	v_max_f32_e32 v144, v134, v135
	v_max3_f32 v131, v131, v137, v144
	v_max_f32_e32 v137, v128, v129
	v_max_f32_e32 v144, v130, v136
	v_max3_f32 v131, v131, v137, v144
	ds_bpermute_b32 v137, v222, v131
	v_sub_f32_e32 v148, v232, v193
	v_add_u32_e32 v149, 0xa800, v238
	v_sub_f32_e32 v144, v233, v195
	v_mul_f32_e32 v144, 0x3fb8aa3b, v144
	s_waitcnt lgkmcnt(0)
	v_max_f32_e32 v131, v131, v137
	ds_bpermute_b32 v137, v223, v131
	v_exp_f32_e32 v144, v144
	v_pk_mul_f32 v[58:59], v[58:59], v[138:139] op_sel_hi:[1,0]
	v_pk_mul_f32 v[56:57], v[56:57], v[138:139] op_sel_hi:[1,0]
	v_pk_mul_f32 v[54:55], v[54:55], v[138:139] op_sel_hi:[1,0]
	s_waitcnt lgkmcnt(0)
	v_max_f32_e32 v137, v131, v137
	v_pk_mul_f32 v[146:147], v[136:137], s[6:7] op_sel_hi:[1,0]
	v_pk_mul_f32 v[78:79], v[78:79], v[144:145] op_sel_hi:[1,0]
	v_fma_f32 v131, v160, s6, -v147
	v_exp_f32_e32 v136, v131
	v_fma_f32 v131, v161, s6, -v147
	v_exp_f32_e32 v164, v131
	v_fma_f32 v131, v162, s6, -v147
	v_exp_f32_e32 v162, v131
	v_fma_f32 v131, v163, s6, -v147
	v_exp_f32_e32 v163, v131
	v_fma_f32 v131, v140, s6, -v147
	v_exp_f32_e32 v165, v131
	v_fma_f32 v131, v141, s6, -v147
	v_exp_f32_e32 v166, v131
	v_fma_f32 v131, v142, s6, -v147
	v_exp_f32_e32 v167, v131
	v_fma_f32 v131, v143, s6, -v147
	v_exp_f32_e32 v168, v131
	v_fma_f32 v131, v132, s6, -v147
	v_fma_f32 v128, v128, s6, -v147
	v_exp_f32_e32 v169, v131
	v_fma_f32 v131, v133, s6, -v147
	v_exp_f32_e32 v173, v128
	v_fma_f32 v128, v129, s6, -v147
	v_exp_f32_e32 v170, v131
	v_fma_f32 v131, v134, s6, -v147
	v_exp_f32_e32 v174, v128
	v_fma_f32 v128, v130, s6, -v147
	v_exp_f32_e32 v171, v131
	v_fma_f32 v131, v135, s6, -v147
	v_exp_f32_e32 v175, v128
	v_sub_f32_e32 v128, v146, v147
	v_exp_f32_e32 v172, v131
	v_exp_f32_e32 v196, v128
	v_cvt_pk_bf16_f32 v128, v169, v170
	v_cvt_pk_bf16_f32 v130, v173, v174
	v_cvt_pk_bf16_f32 v129, v171, v172
	v_cvt_pk_bf16_f32 v131, v175, v196
	v_cvt_pk_bf16_f32 v140, v136, v164
	v_cvt_pk_bf16_f32 v141, v162, v163
	v_cvt_pk_bf16_f32 v142, v165, v166
	v_cvt_pk_bf16_f32 v143, v167, v168
	ds_write2_b64 v149, v[128:129], v[130:131] offset0:104 offset1:108
	v_mul_f32_e32 v128, 0x3fb8aa3b, v148
	ds_write2_b64 v149, v[140:141], v[142:143] offset0:96 offset1:100
	v_exp_f32_e32 v128, v128
	s_waitcnt lgkmcnt(0)
	ds_read_b64_tr_b16 v[134:135], v214 offset:19008
	ds_read_b64_tr_b16 v[132:133], v214 offset:18432
	ds_read_b64_tr_b16 v[158:159], v214 offset:18464
	ds_read_b64_tr_b16 v[160:161], v214 offset:19040
	v_pk_mul_f32 v[86:87], v[86:87], v[128:129] op_sel_hi:[1,0]
	v_pk_mul_f32 v[84:85], v[84:85], v[128:129] op_sel_hi:[1,0]
	v_sub_f32_e32 v129, v231, v137
	v_mul_f32_e32 v129, 0x3fb8aa3b, v129
	ds_read_b128 v[140:143], v213 offset:36864
	ds_read_b128 v[146:149], v213 offset:39168
	ds_read_b128 v[150:153], v213 offset:41472
	ds_read_b128 v[154:157], v213 offset:43776
	v_exp_f32_e32 v130, v129
	v_pk_mul_f32 v[76:77], v[76:77], v[144:145] op_sel_hi:[1,0]
	v_pk_mul_f32 v[90:91], v[90:91], v[128:129] op_sel_hi:[1,0]
	v_pk_mul_f32 v[88:89], v[88:89], v[128:129] op_sel_hi:[1,0]
	v_pk_mul_f32 v[50:51], v[50:51], v[130:131] op_sel_hi:[1,0]
	v_pk_mul_f32 v[48:49], v[48:49], v[130:131] op_sel_hi:[1,0]
	v_pk_mul_f32 v[70:71], v[70:71], v[144:145] op_sel_hi:[1,0]
	v_pk_mul_f32 v[68:69], v[68:69], v[144:145] op_sel_hi:[1,0]
	v_pk_mul_f32 v[52:53], v[52:53], v[138:139] op_sel_hi:[1,0]
	v_pk_mul_f32 v[34:35], v[34:35], v[130:131] op_sel_hi:[1,0]
	v_pk_mul_f32 v[32:33], v[32:33], v[130:131] op_sel_hi:[1,0]
	s_waitcnt lgkmcnt(3)
	v_mfma_f32_16x16x32_bf16 v[84:87], v[132:135], v[140:143], v[84:87]
	v_mul_f32_e64 v82, v82, v128
	v_mul_f32_e64 v83, v83, v128
	v_pk_mul_f32 v[80:81], v[80:81], v[128:129] op_sel_hi:[1,0]
	v_pk_mul_f32 v[94:95], v[94:95], v[128:129] op_sel_hi:[1,0]
	s_waitcnt lgkmcnt(2)
	v_mfma_f32_16x16x32_bf16 v[76:79], v[132:135], v[146:149], v[76:79]
	v_mul_f32_e64 v92, v92, v128
	v_mul_f32_e64 v93, v93, v128
	v_add_f32_e32 v129, 0, v136
	v_add_f32_e32 v129, v164, v129
	s_waitcnt lgkmcnt(1)
	v_mfma_f32_16x16x32_bf16 v[56:59], v[132:135], v[150:153], v[56:59]
	v_add_f32_e32 v129, v162, v129
	v_add_f32_e32 v129, v163, v129
	v_pk_mul_f32 v[66:67], v[66:67], v[144:145] op_sel_hi:[1,0]
	s_waitcnt lgkmcnt(0)
; #define MMA16(b, a, c) __builtin_amdgcn_mfma_f32_16x16x32_bf16((b), (a), (c), 0, 0, 0)
; __device__ __forceinline__ void attn_phase(const Params& p, LAS unsigned char* lds, int G) {
;     ...
;                     o[m][n] = o[m][n] * alpha;
;                 }
;                 ps += __shfl_xor(ps, 16); ps += __shfl_xor(ps, 32);
;                 lrow[m] = lrow[m] * alpha + ps;
;             }
;             asm volatile("s_waitcnt lgkmcnt(0)" ::: "memory");
;             {
; #pragma unroll
;                 for (int k = 0; k < 2; ++k) {
;                     bf16x8 pa[4], vb[4];
; #pragma unroll
;                     for (int m = 0; m < 4; ++m) pa[m] = LDS16(Pl + (16 * m + fr) * 72 + 32 * k + 8 * fq);
; #pragma unroll
;                     for (int n = 0; n < 4; ++n) vb[n] = tr_frag(Vl + (kvh * 64 + 32 * k) * 72 + trb + 16 * n, 72);
; #pragma unroll
;                     for (int n = 0; n < 4; ++n)
; #pragma unroll
;                         for (int m = 0; m < 4; ++m) o[m][n] = MMA16(vb[n], pa[m], o[m][n]);
;                 }
;             }
	v_mfma_f32_16x16x32_bf16 v[48:51], v[132:135], v[154:157], v[48:51]
	ds_read_b64_tr_b16 v[132:133], v214 offset:18496
	ds_read_b64_tr_b16 v[134:135], v214 offset:19072
	v_pk_mul_f32 v[64:65], v[64:65], v[144:145] op_sel_hi:[1,0]
	v_mfma_f32_16x16x32_bf16 v[88:91], v[158:161], v[140:143], v[88:91]
	v_mul_f32_e64 v62, v62, v138
	v_mul_f32_e64 v63, v63, v138
	v_pk_mul_f32 v[60:61], v[60:61], v[138:139] op_sel_hi:[1,0]
	v_pk_mul_f32 v[46:47], v[46:47], v[130:131] op_sel_hi:[1,0]
	v_mfma_f32_16x16x32_bf16 v[68:71], v[158:161], v[146:149], v[68:71]
	v_mul_f32_e64 v44, v44, v130
	v_mul_f32_e64 v45, v45, v130
	v_pk_mul_f32 v[74:75], v[74:75], v[144:145] op_sel_hi:[1,0]
	v_pk_mul_f32 v[72:73], v[72:73], v[144:145] op_sel_hi:[1,0]
	v_mfma_f32_16x16x32_bf16 v[52:55], v[158:161], v[150:153], v[52:55]
	v_mul_f32_e64 v38, v38, v138
	v_mul_f32_e64 v39, v39, v138
	v_pk_mul_f32 v[36:37], v[36:37], v[138:139] op_sel_hi:[1,0]
	v_add_f32_e32 v129, v165, v129
	v_mfma_f32_16x16x32_bf16 v[32:35], v[158:161], v[154:157], v[32:35]
	ds_read_b64_tr_b16 v[160:161], v214 offset:19104
	ds_read_b64_tr_b16 v[158:159], v214 offset:18528
	v_pk_mul_f32 v[42:43], v[42:43], v[130:131] op_sel_hi:[1,0]
	s_waitcnt lgkmcnt(2)
	v_mfma_f32_16x16x32_bf16 v[80:83], v[132:135], v[140:143], v[80:83]
	v_mul_f32_e64 v40, v40, v130
	v_mul_f32_e64 v41, v41, v130
	v_add_f32_e32 v129, v166, v129
	v_add_f32_e32 v129, v167, v129
	v_mfma_f32_16x16x32_bf16 v[64:67], v[132:135], v[146:149], v[64:67]
	v_add_f32_e32 v129, v168, v129
	v_add_f32_e32 v129, v169, v129
	v_add_f32_e32 v129, v170, v129
	v_mfma_f32_16x16x32_bf16 v[60:63], v[132:135], v[150:153], v[60:63]
	v_add_f32_e32 v129, v171, v129
	v_add_f32_e32 v129, v172, v129
	v_add_f32_e32 v129, v173, v129
	v_mfma_f32_16x16x32_bf16 v[44:47], v[132:135], v[154:157], v[44:47]
	ds_read_b64_tr_b16 v[132:133], v214 offset:23040
	ds_read_b64_tr_b16 v[134:135], v214 offset:23616
	v_add_f32_e32 v129, v174, v129
	v_add_f32_e32 v129, v175, v129
	s_waitcnt lgkmcnt(2)
	v_mfma_f32_16x16x32_bf16 v[92:95], v[158:161], v[140:143], v[92:95]
	ds_read_b128 v[140:143], v213 offset:36928
	v_add_f32_e32 v131, v194, v237
	v_fmac_f32_e32 v131, v228, v144
	v_mfma_f32_16x16x32_bf16 v[72:75], v[158:161], v[146:149], v[72:75]
	ds_read_b128 v[146:149], v213 offset:39232
	s_add_i32 s19, s19, 1
	v_add_u32_e32 v225, 64, v225
	v_mfma_f32_16x16x32_bf16 v[36:39], v[158:161], v[150:153], v[36:39]
	ds_read_b128 v[150:153], v213 offset:41536
	v_add_u32_e32 v224, 64, v224
	s_and_b64 vcc, exec, s[10:11]
	v_mfma_f32_16x16x32_bf16 v[40:43], v[158:161], v[154:157], v[40:43]
	ds_read_b128 v[154:157], v213 offset:43840
	ds_read_b64_tr_b16 v[158:159], v214 offset:23072
	ds_read_b64_tr_b16 v[160:161], v214 offset:23648
	s_waitcnt lgkmcnt(5)
	v_mfma_f32_16x16x32_bf16 v[84:87], v[132:135], v[140:143], v[84:87]
	s_waitcnt lgkmcnt(4)
	v_mfma_f32_16x16x32_bf16 v[76:79], v[132:135], v[146:149], v[76:79]
	s_waitcnt lgkmcnt(3)
	v_mfma_f32_16x16x32_bf16 v[56:59], v[132:135], v[150:153], v[56:59]
	s_waitcnt lgkmcnt(2)
	v_mfma_f32_16x16x32_bf16 v[48:51], v[132:135], v[154:157], v[48:51]
	ds_read_b64_tr_b16 v[132:133], v214 offset:23104
	ds_read_b64_tr_b16 v[134:135], v214 offset:23680
	s_waitcnt lgkmcnt(0)
	v_mfma_f32_16x16x32_bf16 v[80:83], v[132:135], v[140:143], v[80:83]
	v_mfma_f32_16x16x32_bf16 v[64:67], v[132:135], v[146:149], v[64:67]
	v_mfma_f32_16x16x32_bf16 v[60:63], v[132:135], v[150:153], v[60:63]
	v_mfma_f32_16x16x32_bf16 v[44:47], v[132:135], v[154:157], v[44:47]
	v_add_f32_e32 v132, v196, v129
	ds_bpermute_b32 v133, v222, v132
	v_add_f32_e32 v129, v139, v145
	v_mfma_f32_16x16x32_bf16 v[88:91], v[158:161], v[140:143], v[88:91]
	v_fmac_f32_e32 v129, v229, v138
	s_waitcnt lgkmcnt(0)
	v_add_f32_e32 v133, v132, v133
	v_mfma_f32_16x16x32_bf16 v[68:71], v[158:161], v[146:149], v[68:71]
	ds_bpermute_b32 v134, v223, v133
	v_add_f32_e32 v132, v192, v234
	v_fmac_f32_e32 v132, v227, v128
	v_mfma_f32_16x16x32_bf16 v[52:55], v[158:161], v[150:153], v[52:55]
	s_waitcnt lgkmcnt(0)
	v_add_f32_e32 v128, v133, v134
	v_fmac_f32_e32 v128, v226, v130
	v_mfma_f32_16x16x32_bf16 v[32:35], v[158:161], v[154:157], v[32:35]
	ds_read_b64_tr_b16 v[158:159], v214 offset:23136
	ds_read_b64_tr_b16 v[160:161], v214 offset:23712
	s_waitcnt lgkmcnt(0)
	v_mfma_f32_16x16x32_bf16 v[92:95], v[158:161], v[140:143], v[92:95]
	v_mfma_f32_16x16x32_bf16 v[72:75], v[158:161], v[146:149], v[72:75]
	v_mfma_f32_16x16x32_bf16 v[36:39], v[158:161], v[150:153], v[36:39]
	v_mfma_f32_16x16x32_bf16 v[40:43], v[158:161], v[154:157], v[40:43]
	s_cbranch_vccnz .LBB0_563
	v_mov_b32_e32 v236, v230
	v_mov_b32_e32 v231, v137
	v_mov_b32_e32 v235, v197
	v_mov_b32_e32 v233, v195
	v_mov_b32_e32 v232, v193
	v_mov_b32_e32 v226, v128
	v_mov_b32_e32 v229, v129
	v_mov_b32_e32 v228, v131
	v_mov_b32_e32 v227, v132
	s_branch .LBB0_543
